# role alternation in phases +3 (attention first / conv last) and +5 (post first / RG-LRU last) for WG blocks with unit-index bit 4 set, on top of ST2
# speedup vs baseline: 1.0065x; 1.0065x over previous
; #define SUB(k, bit) (!(kargs()->li == 1 && (k) == lo) || ((kargs()->submask >> (bit)) & 1u))
; __global__ void __launch_bounds__(NWAVES * 64, 2) fwd(Args args_unused) {
;     ...
;         if (IN(pb + 3)) {
;             PH_PTRS PH_LAYER
;             if (SUB(pb + 3, 0)) {
.LBB0_1363:
	s_or_b64 exec, exec, s[0:1]
	s_waitcnt lgkmcnt(0)
	s_barrier
.LBB0_1364:
	v_readlane_b32 s99, v254, 3
	s_nop 3
	s_bfe_u32 s99, s99, 0x10004
	s_cmp_eq_u32 s99, 1
	s_cselect_b32 s98, 0, 2

; __device__ __forceinline__ unsigned f2bf(float f) { return pk2(f, 0.f) & 0xffffu; }
; __device__ __forceinline__ float rcpf_(float x) { return __builtin_amdgcn_rcpf(x); }
; #define LDS_WAIT() asm volatile("s_waitcnt lgkmcnt(0)" ::: "memory")
; __global__ void __launch_bounds__(NWAVES * 64, 2) fwd(Args args_unused) {
;     ...
;                     float o = 0.f;
;                     const int jn = t / dil + 1;
;                     for (int j = 0; j < jn; ++j) o += pbuf[j] * bf2f(*ZP(Z, rowS + (t - dil * j), ZV + g * 512 + hh * 64 + lane));
;                     { const float* vc = cache + (size_t)(wb + t) * 1024 + 512 + hh * 64 + lane; const size_t vstep = (size_t)dil * 1024;
; #pragma unroll 8
;                       for (int j = jn; j <= 128; ++j) o += pbuf[j] * vc[-(ptrdiff_t)(j * vstep)]; }
;                     OG[((size_t)g * M + rowS + t) * 512 + hh * 64 + lane] = (bf16)f2bf(o * rcpf_(sm));
;                     if (lane == 0) LSE[((size_t)g * M + rowS + t) * 8 + hh] = mx + __logf(sm);
;                     LDS_WAIT(); asm volatile("" ::: "memory");
;                 }
;                 __syncthreads();
.LBB0_1516:
	s_add_i32 s4, s15, 9
	s_lshl_b32 s8, s4, s14
	s_add_i32 s17, s15, 10
	s_lshl_b64 s[4:5], s[8:9], 2
	s_lshl_b32 s8, s17, s14
	v_mov_b32_e32 v11, s5
	v_subrev_co_u32_e64 v18, s[4:5], s4, v12
	s_add_i32 s20, s15, 11
	s_lshl_b64 s[18:19], s[8:9], 2
	v_subb_co_u32_e64 v19, s[4:5], v13, v11, s[4:5]
	s_lshl_b32 s8, s20, s14
	v_mov_b32_e32 v11, s19
	v_subrev_co_u32_e64 v20, s[4:5], s18, v12
	s_add_i32 s22, s15, 12
	s_lshl_b64 s[20:21], s[8:9], 2
	v_subb_co_u32_e64 v21, s[4:5], v13, v11, s[4:5]
	s_lshl_b32 s8, s22, s14
	v_mov_b32_e32 v11, s21
	v_subrev_co_u32_e64 v22, s[4:5], s20, v12
	s_add_i32 s23, s15, 13
	s_lshl_b64 s[18:19], s[8:9], 2
	v_subb_co_u32_e64 v23, s[4:5], v13, v11, s[4:5]
	s_lshl_b32 s8, s23, s14
	global_load_dword v17, v[18:19], off offset:2048
	global_load_dword v26, v[20:21], off offset:2048
	v_mov_b32_e32 v11, s19
	v_subrev_co_u32_e64 v18, s[4:5], s18, v12
	s_add_i32 s41, s15, 14
	s_lshl_b64 s[20:21], s[8:9], 2
	v_subb_co_u32_e64 v19, s[4:5], v13, v11, s[4:5]
	s_lshl_b32 s8, s41, s14
	v_mov_b32_e32 v11, s21
	v_subrev_co_u32_e64 v20, s[4:5], s20, v12
	s_add_i32 s42, s15, 15
	s_lshl_b64 s[18:19], s[8:9], 2
	v_subb_co_u32_e64 v21, s[4:5], v13, v11, s[4:5]
	s_lshl_b32 s8, s42, s14
	global_load_dword v27, v[22:23], off offset:2048
	global_load_dword v28, v[18:19], off offset:2048
	v_mov_b32_e32 v11, s19
	v_subrev_co_u32_e64 v18, s[4:5], s18, v12
	s_add_i32 s43, s15, 16
	s_lshl_b64 s[20:21], s[8:9], 2
	v_subb_co_u32_e64 v19, s[4:5], v13, v11, s[4:5]
	s_lshl_b32 s8, s43, s14
	v_mov_b32_e32 v11, s21
	v_subrev_co_u32_e64 v22, s[4:5], s20, v12
	s_lshl_b64 s[18:19], s[8:9], 2
	global_load_dword v29, v[20:21], off offset:2048
	global_load_dword v30, v[18:19], off offset:2048
	v_subb_co_u32_e64 v23, s[4:5], v13, v11, s[4:5]
	v_mov_b32_e32 v11, s19
	v_subrev_co_u32_e64 v18, s[4:5], s18, v12
	v_mov_b32_e32 v24, s16
	s_nop 0
	v_subb_co_u32_e64 v19, s[4:5], v13, v11, s[4:5]
	global_load_dword v11, v[22:23], off offset:2048
	global_load_dword v31, v[18:19], off offset:2048
	ds_read2_b32 v[18:19], v24 offset1:1
	ds_read2_b32 v[20:21], v24 offset0:2 offset1:3
	ds_read2_b32 v[22:23], v24 offset0:4 offset1:5
	ds_read2_b32 v[24:25], v24 offset0:6 offset1:7
	s_add_i32 s15, s15, 8
	s_add_i32 s16, s16, 32
	s_cmpk_gt_u32 s15, 0x77
	s_waitcnt vmcnt(7) lgkmcnt(3)
	v_fmac_f32_e32 v14, v18, v17
	s_waitcnt vmcnt(6)
	v_fmac_f32_e32 v14, v19, v26
	s_waitcnt vmcnt(5) lgkmcnt(2)
	v_fmac_f32_e32 v14, v20, v27
	s_waitcnt vmcnt(4)
	v_fmac_f32_e32 v14, v21, v28
	s_waitcnt vmcnt(3) lgkmcnt(1)
	v_fmac_f32_e32 v14, v22, v29
	s_waitcnt vmcnt(2)
	v_fmac_f32_e32 v14, v23, v30
	s_waitcnt vmcnt(1) lgkmcnt(0)
	v_fmac_f32_e32 v14, v24, v11
	s_waitcnt vmcnt(0)
	v_fmac_f32_e32 v14, v25, v31
	s_cbranch_scc0 .LBB0_1516
	v_add_f32_e32 v11, v15, v16
	v_rcp_f32_e32 v12, v11
	s_mul_i32 s4, s39, 0x8100
	s_add_i32 s4, s4, s40
	s_ashr_i32 s5, s4, 31
	s_or_b64 s[6:7], s[4:5], s[6:7]
	v_mul_f32_e32 v12, v12, v14
	s_lshl_b64 s[4:5], s[6:7], 10
	v_cvt_pk_bf16_f32 v14, v12, v3
	v_lshl_add_u64 v[12:13], v[6:7], 0, s[4:5]
	global_store_short v[12:13], v14, off
	s_and_saveexec_b64 s[14:15], vcc
	s_cbranch_execz .LBB0_1498
	v_cmp_gt_f32_e64 s[4:5], s36, v11
	s_lshl_b64 s[6:7], s[6:7], 5
	s_add_u32 s16, s30, s6
	v_cndmask_b32_e64 v12, 0, 32, s[4:5]
	v_ldexp_f32 v11, v11, v12
	v_log_f32_e32 v11, v11
	s_addc_u32 s17, s31, s7
	v_mul_f32_e32 v12, 0x3f317217, v11
	v_fma_f32 v12, v11, s37, -v12
	v_fmac_f32_e32 v12, 0x3377d1cf, v11
	v_fmac_f32_e32 v12, 0x3f317217, v11
	v_cmp_lt_f32_e64 s[6:7], |v11|, s38
	s_nop 1
	v_cndmask_b32_e64 v11, v11, v12, s[6:7]
	v_cndmask_b32_e64 v12, 0, v74, s[4:5]
	v_sub_f32_e32 v11, v11, v12
	v_add_f32_e32 v2, v2, v11
	global_store_dword v3, v2, s[16:17]
	s_branch .LBB0_1498
.LBB0_1519:
	s_cmp_lg_u32 s98, 0
	s_cbranch_scc1 .Lro_fin_0
	s_mov_b32 s98, 1
	s_branch .Lro_again_0
.Lro_fin_0:
	s_barrier

; #define SUB(k, bit) (!(kargs()->li == 1 && (k) == lo) || ((kargs()->submask >> (bit)) & 1u))
; __global__ void __launch_bounds__(NWAVES * 64, 2) fwd(Args args_unused) {
;     ...
;         if (IN(pb + 3)) {
;             PH_PTRS PH_LAYER
;             if (SUB(pb + 3, 0)) {
.LBB0_3388:
	s_or_b64 exec, exec, s[0:1]
	s_waitcnt lgkmcnt(0)
	s_barrier
.LBB0_3389:
	v_readlane_b32 s99, v254, 3
	s_nop 3
	s_bfe_u32 s99, s99, 0x10004
	s_cmp_eq_u32 s99, 1
	s_cselect_b32 s98, 0, 2

; __device__ __forceinline__ unsigned f2bf(float f) { return pk2(f, 0.f) & 0xffffu; }
; __device__ __forceinline__ float rcpf_(float x) { return __builtin_amdgcn_rcpf(x); }
; #define LDS_WAIT() asm volatile("s_waitcnt lgkmcnt(0)" ::: "memory")
; __global__ void __launch_bounds__(NWAVES * 64, 2) fwd(Args args_unused) {
;     ...
;                     float o = 0.f;
;                     const int jn = t / dil + 1;
;                     for (int j = 0; j < jn; ++j) o += pbuf[j] * bf2f(*ZP(Z, rowS + (t - dil * j), ZV + g * 512 + hh * 64 + lane));
;                     { const float* vc = cache + (size_t)(wb + t) * 1024 + 512 + hh * 64 + lane; const size_t vstep = (size_t)dil * 1024;
; #pragma unroll 8
;                       for (int j = jn; j <= 128; ++j) o += pbuf[j] * vc[-(ptrdiff_t)(j * vstep)]; }
;                     OG[((size_t)g * M + rowS + t) * 512 + hh * 64 + lane] = (bf16)f2bf(o * rcpf_(sm));
;                     if (lane == 0) LSE[((size_t)g * M + rowS + t) * 8 + hh] = mx + __logf(sm);
;                     LDS_WAIT(); asm volatile("" ::: "memory");
;                 }
;                 __syncthreads();
.LBB0_3541:
	s_add_i32 s4, s15, 9
	s_lshl_b32 s8, s4, s14
	s_add_i32 s17, s15, 10
	s_lshl_b64 s[4:5], s[8:9], 2
	s_lshl_b32 s8, s17, s14
	v_mov_b32_e32 v11, s5
	v_subrev_co_u32_e64 v18, s[4:5], s4, v12
	s_add_i32 s20, s15, 11
	s_lshl_b64 s[18:19], s[8:9], 2
	v_subb_co_u32_e64 v19, s[4:5], v13, v11, s[4:5]
	s_lshl_b32 s8, s20, s14
	v_mov_b32_e32 v11, s19
	v_subrev_co_u32_e64 v20, s[4:5], s18, v12
	s_add_i32 s22, s15, 12
	s_lshl_b64 s[20:21], s[8:9], 2
	v_subb_co_u32_e64 v21, s[4:5], v13, v11, s[4:5]
	s_lshl_b32 s8, s22, s14
	v_mov_b32_e32 v11, s21
	v_subrev_co_u32_e64 v22, s[4:5], s20, v12
	s_add_i32 s23, s15, 13
	s_lshl_b64 s[18:19], s[8:9], 2
	v_subb_co_u32_e64 v23, s[4:5], v13, v11, s[4:5]
	s_lshl_b32 s8, s23, s14
	global_load_dword v17, v[18:19], off offset:2048
	global_load_dword v26, v[20:21], off offset:2048
	v_mov_b32_e32 v11, s19
	v_subrev_co_u32_e64 v18, s[4:5], s18, v12
	s_add_i32 s41, s15, 14
	s_lshl_b64 s[20:21], s[8:9], 2
	v_subb_co_u32_e64 v19, s[4:5], v13, v11, s[4:5]
	s_lshl_b32 s8, s41, s14
	v_mov_b32_e32 v11, s21
	v_subrev_co_u32_e64 v20, s[4:5], s20, v12
	s_add_i32 s42, s15, 15
	s_lshl_b64 s[18:19], s[8:9], 2
	v_subb_co_u32_e64 v21, s[4:5], v13, v11, s[4:5]
	s_lshl_b32 s8, s42, s14
	global_load_dword v27, v[22:23], off offset:2048
	global_load_dword v28, v[18:19], off offset:2048
	v_mov_b32_e32 v11, s19
	v_subrev_co_u32_e64 v18, s[4:5], s18, v12
	s_add_i32 s43, s15, 16
	s_lshl_b64 s[20:21], s[8:9], 2
	v_subb_co_u32_e64 v19, s[4:5], v13, v11, s[4:5]
	s_lshl_b32 s8, s43, s14
	v_mov_b32_e32 v11, s21
	v_subrev_co_u32_e64 v22, s[4:5], s20, v12
	s_lshl_b64 s[18:19], s[8:9], 2
	global_load_dword v29, v[20:21], off offset:2048
	global_load_dword v30, v[18:19], off offset:2048
	v_subb_co_u32_e64 v23, s[4:5], v13, v11, s[4:5]
	v_mov_b32_e32 v11, s19
	v_subrev_co_u32_e64 v18, s[4:5], s18, v12
	v_mov_b32_e32 v24, s16
	s_nop 0
	v_subb_co_u32_e64 v19, s[4:5], v13, v11, s[4:5]
	global_load_dword v11, v[22:23], off offset:2048
	global_load_dword v31, v[18:19], off offset:2048
	ds_read2_b32 v[18:19], v24 offset1:1
	ds_read2_b32 v[20:21], v24 offset0:2 offset1:3
	ds_read2_b32 v[22:23], v24 offset0:4 offset1:5
	ds_read2_b32 v[24:25], v24 offset0:6 offset1:7
	s_add_i32 s15, s15, 8
	s_add_i32 s16, s16, 32
	s_cmpk_lt_u32 s15, 0x78
	s_waitcnt vmcnt(7) lgkmcnt(3)
	v_fmac_f32_e32 v14, v18, v17
	s_waitcnt vmcnt(6)
	v_fmac_f32_e32 v14, v19, v26
	s_waitcnt vmcnt(5) lgkmcnt(2)
	v_fmac_f32_e32 v14, v20, v27
	s_waitcnt vmcnt(4)
	v_fmac_f32_e32 v14, v21, v28
	s_waitcnt vmcnt(3) lgkmcnt(1)
	v_fmac_f32_e32 v14, v22, v29
	s_waitcnt vmcnt(2)
	v_fmac_f32_e32 v14, v23, v30
	s_waitcnt vmcnt(1) lgkmcnt(0)
	v_fmac_f32_e32 v14, v24, v11
	s_waitcnt vmcnt(0)
	v_fmac_f32_e32 v14, v25, v31
	s_cbranch_scc1 .LBB0_3541
	v_add_f32_e32 v11, v15, v16
	v_rcp_f32_e32 v12, v11
	s_mul_i32 s4, s39, 0x8100
	s_add_i32 s4, s4, s40
	s_ashr_i32 s5, s4, 31
	s_or_b64 s[6:7], s[4:5], s[6:7]
	v_mul_f32_e32 v12, v12, v14
	s_lshl_b64 s[4:5], s[6:7], 10
	v_cvt_pk_bf16_f32 v14, v12, v3
	v_lshl_add_u64 v[12:13], v[6:7], 0, s[4:5]
	global_store_short v[12:13], v14, off
	s_and_saveexec_b64 s[14:15], vcc
	s_cbranch_execz .LBB0_3523
	v_cmp_gt_f32_e64 s[4:5], s36, v11
	s_lshl_b64 s[6:7], s[6:7], 5
	s_add_u32 s16, s30, s6
	v_cndmask_b32_e64 v12, 0, 32, s[4:5]
	v_ldexp_f32 v11, v11, v12
	v_log_f32_e32 v11, v11
	s_addc_u32 s17, s31, s7
	v_mul_f32_e32 v12, 0x3f317217, v11
	v_fma_f32 v12, v11, s37, -v12
	v_fmac_f32_e32 v12, 0x3377d1cf, v11
	v_fmac_f32_e32 v12, 0x3f317217, v11
	v_cmp_lt_f32_e64 s[6:7], |v11|, s38
	s_nop 1
	v_cndmask_b32_e64 v11, v11, v12, s[6:7]
	v_cndmask_b32_e64 v12, 0, v74, s[4:5]
	v_sub_f32_e32 v11, v11, v12
	v_add_f32_e32 v2, v2, v11
	global_store_dword v3, v2, s[16:17]
	s_branch .LBB0_3523
.LBB0_3544:
	s_cmp_lg_u32 s98, 0
	s_cbranch_scc1 .Lro_fin_1
	s_mov_b32 s98, 1
	s_branch .Lro_again_1
.Lro_fin_1:
	s_barrier
